# DMA version + V fragments for the first two PV MFMAs read early (during QK chain 2)
# baseline (speedup 1.0000x reference)
.LBB0_398:
	ds_read_b128 v[222:225], v208 offset:40960
	ds_read_b128 v[226:229], v208 offset:45056
	v_exp_f32_e32 v148, v80
	v_exp_f32_e32 v149, v81
	s_waitcnt lgkmcnt(1)
	v_mfma_f32_32x32x16_bf16 v[112:127], v[222:225], v[64:67], v[96:111]
	ds_read_b128 v[230:233], v209 offset:40960
	ds_read_b128 v[182:185], v209 offset:45056
	ds_read_b128 v[150:153], v210 offset:40960
	v_exp_f32_e32 v154, v84
	v_exp_f32_e32 v155, v85
	v_exp_f32_e32 v158, v86
	v_exp_f32_e32 v159, v87
	v_exp_f32_e32 v156, v90
	v_exp_f32_e32 v157, v91
	s_waitcnt lgkmcnt(2)
	v_mfma_f32_32x32x16_bf16 v[112:127], v[230:233], v[68:71], v[112:127]
	ds_read_b128 v[234:237], v210 offset:45056
	ds_read_b128 v[218:221], v211 offset:45056
	ds_read_b128 v[160:163], v211 offset:40960
	v_exp_f32_e32 v166, v94
	v_exp_f32_e32 v167, v95
	s_waitcnt lgkmcnt(3)
	v_mfma_f32_32x32x16_bf16 v[112:127], v[150:153], v[72:75], v[112:127]
	v_exp_f32_e32 v152, v82
	v_exp_f32_e32 v153, v83
	v_exp_f32_e32 v150, v88
	v_exp_f32_e32 v151, v89
	s_waitcnt lgkmcnt(0)
	v_mfma_f32_32x32x16_bf16 v[112:127], v[160:163], v[76:79], v[112:127]
	ds_read_b64_tr_b16 v[186:187], v203 offset:0
	ds_read_b64_tr_b16 v[188:189], v203 offset:0x800
	ds_read_b64_tr_b16 v[214:215], v203 offset:0x200
	ds_read_b64_tr_b16 v[216:217], v203 offset:0xa00
	v_exp_f32_e32 v162, v92
	v_exp_f32_e32 v163, v93
	v_mfma_f32_32x32x16_bf16 v[80:95], v[226:229], v[64:67], v[96:111]
	v_add_f32_e32 v238, v164, v148
	v_add_f32_e32 v238, v149, v238
	v_add_f32_e32 v238, v152, v238
	v_add_f32_e32 v238, v153, v238
	v_add_f32_e32 v238, v154, v238
	v_add_f32_e32 v238, v155, v238
	v_add_f32_e32 v238, v158, v238
	v_mfma_f32_32x32x16_bf16 v[80:95], v[182:185], v[68:71], v[80:95]
	v_add_f32_e32 v238, v159, v238
	v_add_f32_e32 v238, v150, v238
	v_add_f32_e32 v238, v151, v238
	v_add_f32_e32 v238, v156, v238
	v_add_f32_e32 v238, v157, v238
	v_add_f32_e32 v238, v162, v238
	v_add_f32_e32 v238, v163, v238
	v_mfma_f32_32x32x16_bf16 v[80:95], v[234:237], v[72:75], v[80:95]
	v_add_f32_e32 v239, v166, v238
	v_add_f32_e32 v239, v167, v239
	v_mov_b32_e32 v240, v239
	s_nop 1
	v_permlane32_swap_b32_e32 v239, v240
	v_add_f32_e32 v164, v239, v240
	v_cmp_ge_f32_e32 vcc, s99, v164
	v_mfma_f32_32x32x16_bf16 v[80:95], v[218:221], v[76:79], v[80:95]
	s_cmp_eq_u64 vcc, exec
	s_cbranch_scc0 .LBB0_405
.LBB0_400:
	v_cvt_pk_bf16_f32 v182, v148, v149
	v_cvt_pk_bf16_f32 v183, v152, v153
	v_cvt_pk_bf16_f32 v184, v154, v155
	v_cvt_pk_bf16_f32 v185, v158, v159
	v_cvt_pk_bf16_f32 v160, v150, v151
	v_cvt_pk_bf16_f32 v161, v156, v157
	v_cvt_pk_bf16_f32 v162, v162, v163
	v_cvt_pk_bf16_f32 v163, v166, v167
	s_cmpk_lt_u32 s51, 0x100
	s_cselect_b32 s0, s38, s34
	s_add_i32 s3, s0, s51
	s_mul_i32 s0, s3, 0x1800
	s_mul_hi_i32 s1, s3, 0x1800
	s_add_u32 s0, s39, s0
	s_addc_u32 s1, s42, s1
	s_max_i32 vcc_lo, s100, 0
	s_add_i32 vcc_lo, vcc_lo, s96
	s_add_i32 m0, vcc_lo, 0x4100
	s_nop 0
	global_load_lds_dwordx4 v129, s[0:1]
	s_add_i32 m0, vcc_lo, 0x4500
	s_nop 0
	global_load_lds_dwordx4 v130, s[0:1]
	s_mul_i32 s0, s3, 0x1800
	s_mul_hi_i32 s1, s3, 0x1800
	s_add_u32 s0, s28, s0
	s_addc_u32 s1, s29, s1
	s_max_i32 vcc_lo, s101, 0
	s_add_i32 vcc_lo, vcc_lo, s97
	s_add_i32 m0, vcc_lo, 0xa100
	s_nop 0
	global_load_lds_dwordx4 v128, s[0:1]
	ds_read_b64_tr_b16 v[218:219], v203 offset:0x400
	ds_read_b64_tr_b16 v[220:221], v203 offset:0xc00
	ds_read_b64_tr_b16 v[222:223], v203 offset:0x600
	ds_read_b64_tr_b16 v[224:225], v203 offset:0xe00
	ds_read_b64_tr_b16 v[226:227], v203 offset:0x1000
	ds_read_b64_tr_b16 v[228:229], v203 offset:0x1800
	ds_read_b64_tr_b16 v[230:231], v203 offset:0x1200
	ds_read_b64_tr_b16 v[232:233], v203 offset:0x1a00
	ds_read_b64_tr_b16 v[234:235], v203 offset:0x1400
	ds_read_b64_tr_b16 v[236:237], v203 offset:0x1c00
	ds_read_b64_tr_b16 v[238:239], v203 offset:0x1600
	ds_read_b64_tr_b16 v[240:241], v203 offset:0x1e00
	s_nop 0
	s_waitcnt lgkmcnt(12)
	v_exp_f32_e32 v112, v112
	v_mfma_f32_32x32x16_bf16 v[0:15], v[144:147], v[186:189], v[0:15]
	v_exp_f32_e32 v113, v113
	v_exp_f32_e32 v114, v114
	v_exp_f32_e32 v115, v115
	v_exp_f32_e32 v116, v116
	v_exp_f32_e32 v117, v117
	v_exp_f32_e32 v118, v118
	v_exp_f32_e32 v119, v119
	v_mfma_f32_32x32x16_bf16 v[48:63], v[144:147], v[214:217], v[48:63]
	v_exp_f32_e32 v120, v120
	v_exp_f32_e32 v121, v121
	v_exp_f32_e32 v122, v122
	v_exp_f32_e32 v123, v123
	v_exp_f32_e32 v124, v124
	v_exp_f32_e32 v125, v125
	v_exp_f32_e32 v126, v126
	s_waitcnt lgkmcnt(8)
	v_mfma_f32_32x32x16_bf16 v[32:47], v[144:147], v[218:221], v[32:47]
	v_exp_f32_e32 v127, v127
	v_mfma_f32_32x32x16_bf16 v[16:31], v[144:147], v[222:225], v[16:31]
	ds_read_b64_tr_b16 v[144:145], v203 offset:0x2000
	ds_read_b64_tr_b16 v[146:147], v203 offset:0x2800
	ds_read_b64_tr_b16 v[186:187], v203 offset:0x2200
	ds_read_b64_tr_b16 v[188:189], v203 offset:0x2a00
	ds_read_b64_tr_b16 v[214:215], v203 offset:0x2400
	ds_read_b64_tr_b16 v[216:217], v203 offset:0x2c00
	ds_read_b64_tr_b16 v[218:219], v203 offset:0x2600
	ds_read_b64_tr_b16 v[220:221], v203 offset:0x2e00
	s_waitcnt lgkmcnt(8)
	ds_read_b64_tr_b16 v[222:223], v203 offset:0x3000
	ds_read_b64_tr_b16 v[224:225], v203 offset:0x3800
	s_nop 0
	v_mfma_f32_32x32x16_bf16 v[0:15], v[140:143], v[226:229], v[0:15]
	ds_read_b64_tr_b16 v[226:227], v203 offset:0x3200
	ds_read_b64_tr_b16 v[228:229], v203 offset:0x3a00
	v_mfma_f32_32x32x16_bf16 v[48:63], v[140:143], v[230:233], v[48:63]
	ds_read_b64_tr_b16 v[230:231], v203 offset:0x3400
	ds_read_b64_tr_b16 v[232:233], v203 offset:0x3c00
	v_mfma_f32_32x32x16_bf16 v[32:47], v[140:143], v[234:237], v[32:47]
	ds_read_b64_tr_b16 v[234:235], v203 offset:0x3600
	ds_read_b64_tr_b16 v[236:237], v203 offset:0x3e00
	s_waitcnt lgkmcnt(8)
	s_nop 0
	s_waitcnt lgkmcnt(0)
	v_mfma_f32_32x32x16_bf16 v[16:31], v[140:143], v[238:241], v[16:31]
	v_add_f32_e32 v140, 0, v112
	v_add_f32_e32 v140, v113, v140
	v_add_f32_e32 v140, v114, v140
	v_add_f32_e32 v140, v115, v140
	v_add_f32_e32 v140, v116, v140
	v_add_f32_e32 v140, v117, v140
	v_add_f32_e32 v140, v118, v140
	v_mfma_f32_32x32x16_bf16 v[0:15], v[182:185], v[144:147], v[0:15]
	v_add_f32_e32 v140, v119, v140
	v_add_f32_e32 v140, v120, v140
	v_add_f32_e32 v140, v121, v140
	v_add_f32_e32 v140, v122, v140
	v_add_f32_e32 v140, v123, v140
	v_add_f32_e32 v140, v124, v140
	v_add_f32_e32 v140, v125, v140
	v_mfma_f32_32x32x16_bf16 v[48:63], v[182:185], v[186:189], v[48:63]
	v_add_f32_e32 v140, v126, v140
	v_add_f32_e32 v165, v127, v140
	v_cvt_pk_bf16_f32 v144, v112, v113
	v_cvt_pk_bf16_f32 v145, v114, v115
	v_cvt_pk_bf16_f32 v146, v116, v117
	v_cvt_pk_bf16_f32 v147, v118, v119
	v_cvt_pk_bf16_f32 v140, v120, v121
	v_mfma_f32_32x32x16_bf16 v[32:47], v[182:185], v[214:217], v[32:47]
	v_cvt_pk_bf16_f32 v141, v122, v123
	v_cvt_pk_bf16_f32 v142, v124, v125
	v_cvt_pk_bf16_f32 v143, v126, v127
	v_mfma_f32_32x32x16_bf16 v[16:31], v[182:185], v[218:221], v[16:31]
	s_waitcnt vmcnt(3)
	s_waitcnt lgkmcnt(0)
	s_barrier
	v_mfma_f32_32x32x16_bf16 v[0:15], v[160:163], v[222:225], v[0:15]
	v_mfma_f32_32x32x16_bf16 v[48:63], v[160:163], v[226:229], v[48:63]
	v_mfma_f32_32x32x16_bf16 v[32:47], v[160:163], v[230:233], v[32:47]
	v_mfma_f32_32x32x16_bf16 v[16:31], v[160:163], v[234:237], v[16:31]
	v_add_u32_e32 v208, s101, v208
	v_add_u32_e32 v209, s101, v209
	v_add_u32_e32 v210, s101, v210
	v_add_u32_e32 v211, s101, v211
	ds_read_b128 v[160:163], v208 offset:32768
	ds_read_b128 v[222:225], v208 offset:36864
	v_exp_f32_e32 v166, v84
	v_exp_f32_e32 v167, v85
	s_waitcnt lgkmcnt(1)
	v_mfma_f32_32x32x16_bf16 v[112:127], v[160:163], v[64:67], v[96:111]
	ds_read_b128 v[160:163], v209 offset:32768
	ds_read_b128 v[226:229], v209 offset:36864
	ds_read_b128 v[238:241], v210 offset:36864
	ds_read_b128 v[182:185], v210 offset:32768
	ds_read_b128 v[242:245], v211 offset:36864
	ds_read_b128 v[188:191], v211 offset:32768
	v_exp_f32_e32 v186, v90
	v_exp_f32_e32 v187, v91
	s_andn2_b64 s[0:1], s[6:7], exec
	s_and_b64 s[6:7], s[8:9], exec
	s_or_b64 s[6:7], s[0:1], s[6:7]
	s_waitcnt lgkmcnt(5)
	v_mfma_f32_32x32x16_bf16 v[112:127], v[160:163], v[68:71], v[112:127]
	v_exp_f32_e32 v160, v80
	v_exp_f32_e32 v161, v81
	v_exp_f32_e32 v162, v82
	v_exp_f32_e32 v163, v83
	v_add_f32_e32 v80, v160, v165
	v_add_f32_e32 v80, v161, v80
	v_add_f32_e32 v165, v162, v80
	s_waitcnt lgkmcnt(2)
	v_mfma_f32_32x32x16_bf16 v[112:127], v[182:185], v[72:75], v[112:127]
	v_exp_f32_e32 v182, v86
	v_exp_f32_e32 v183, v87
	v_exp_f32_e32 v184, v88
	v_exp_f32_e32 v185, v89
	v_add_f32_e32 v165, v163, v165
	v_add_f32_e32 v165, v166, v165
	v_add_f32_e32 v165, v167, v165
	s_waitcnt lgkmcnt(0)
	v_mfma_f32_32x32x16_bf16 v[112:127], v[188:191], v[76:79], v[112:127]
	ds_read_b64_tr_b16 v[132:133], v202 offset:0
	ds_read_b64_tr_b16 v[134:135], v202 offset:0x800
	ds_read_b64_tr_b16 v[136:137], v202 offset:0x200
	ds_read_b64_tr_b16 v[138:139], v202 offset:0xa00
	v_exp_f32_e32 v188, v92
	v_exp_f32_e32 v189, v93
	v_exp_f32_e32 v190, v94
	v_exp_f32_e32 v191, v95
	v_add_f32_e32 v165, v182, v165
	v_add_f32_e32 v165, v183, v165
	v_add_f32_e32 v165, v184, v165
	v_mfma_f32_32x32x16_bf16 v[80:95], v[222:225], v[64:67], v[96:111]
	v_add_f32_e32 v165, v185, v165
	v_add_f32_e32 v165, v186, v165
	v_add_f32_e32 v165, v187, v165
	v_add_f32_e32 v165, v188, v165
	v_add_f32_e32 v165, v189, v165
	v_add_f32_e32 v165, v190, v165
	v_add_f32_e32 v165, v191, v165
	v_mfma_f32_32x32x16_bf16 v[80:95], v[226:229], v[68:71], v[80:95]
	v_mov_b32_e32 v179, v165
	s_nop 1
	v_permlane32_swap_b32_e32 v165, v179
	v_add_f32_e64 v178, v164, v178
	v_add_f32_e64 v179, v165, v179
	v_cmp_ge_f32_e32 vcc, s99, v179
	s_cmp_eq_u64 vcc, exec
	v_mfma_f32_32x32x16_bf16 v[80:95], v[238:241], v[72:75], v[80:95]
	v_mfma_f32_32x32x16_bf16 v[80:95], v[242:245], v[76:79], v[80:95]
	s_cbranch_scc0 .LBB0_408

.LBB0_403:
	v_add_f32_e32 v178, v179, v178
	ds_read_b64_tr_b16 v[214:215], v202 offset:0x400
	ds_read_b64_tr_b16 v[216:217], v202 offset:0xc00
	ds_read_b64_tr_b16 v[218:219], v202 offset:0x600
	ds_read_b64_tr_b16 v[220:221], v202 offset:0xe00
	ds_read_b64_tr_b16 v[222:223], v202 offset:0x1000
	ds_read_b64_tr_b16 v[224:225], v202 offset:0x1800
	ds_read_b64_tr_b16 v[226:227], v202 offset:0x1200
	ds_read_b64_tr_b16 v[228:229], v202 offset:0x1a00
	ds_read_b64_tr_b16 v[230:231], v202 offset:0x1400
	ds_read_b64_tr_b16 v[232:233], v202 offset:0x1c00
	ds_read_b64_tr_b16 v[234:235], v202 offset:0x1600
	ds_read_b64_tr_b16 v[236:237], v202 offset:0x1e00
	s_nop 0
	s_waitcnt lgkmcnt(12)
	v_exp_f32_e32 v112, v112
	v_mfma_f32_32x32x16_bf16 v[0:15], v[144:147], v[132:135], v[0:15]
	v_exp_f32_e32 v113, v113
	v_exp_f32_e32 v114, v114
	v_exp_f32_e32 v115, v115
	v_exp_f32_e32 v116, v116
	v_exp_f32_e32 v117, v117
	v_exp_f32_e32 v118, v118
	v_exp_f32_e32 v119, v119
	v_mfma_f32_32x32x16_bf16 v[48:63], v[144:147], v[136:139], v[48:63]
	v_exp_f32_e32 v120, v120
	v_exp_f32_e32 v121, v121
	v_exp_f32_e32 v122, v122
	v_exp_f32_e32 v123, v123
	v_exp_f32_e32 v124, v124
	v_exp_f32_e32 v125, v125
	v_exp_f32_e32 v126, v126
	s_waitcnt lgkmcnt(8)
	v_mfma_f32_32x32x16_bf16 v[32:47], v[144:147], v[214:217], v[32:47]
	v_exp_f32_e32 v127, v127
	s_addk_i32 s51, 0x80
	s_add_i32 s50, s50, 2
	s_and_b64 vcc, exec, s[8:9]
	v_mfma_f32_32x32x16_bf16 v[16:31], v[144:147], v[218:221], v[16:31]
	ds_read_b64_tr_b16 v[144:145], v202 offset:0x2000
	ds_read_b64_tr_b16 v[146:147], v202 offset:0x2800
	ds_read_b64_tr_b16 v[182:183], v202 offset:0x2200
	ds_read_b64_tr_b16 v[184:185], v202 offset:0x2a00
	ds_read_b64_tr_b16 v[186:187], v202 offset:0x2400
	ds_read_b64_tr_b16 v[188:189], v202 offset:0x2c00
	ds_read_b64_tr_b16 v[214:215], v202 offset:0x2600
	ds_read_b64_tr_b16 v[216:217], v202 offset:0x2e00
	s_waitcnt lgkmcnt(8)
	ds_read_b64_tr_b16 v[218:219], v202 offset:0x3000
	ds_read_b64_tr_b16 v[220:221], v202 offset:0x3800
	s_nop 0
	v_mfma_f32_32x32x16_bf16 v[0:15], v[140:143], v[222:225], v[0:15]
	ds_read_b64_tr_b16 v[222:223], v202 offset:0x3200
	ds_read_b64_tr_b16 v[224:225], v202 offset:0x3a00
	v_mfma_f32_32x32x16_bf16 v[48:63], v[140:143], v[226:229], v[48:63]
	ds_read_b64_tr_b16 v[226:227], v202 offset:0x3400
	ds_read_b64_tr_b16 v[228:229], v202 offset:0x3c00
	v_mfma_f32_32x32x16_bf16 v[32:47], v[140:143], v[230:233], v[32:47]
	ds_read_b64_tr_b16 v[230:231], v202 offset:0x3600
	ds_read_b64_tr_b16 v[232:233], v202 offset:0x3e00
	s_waitcnt lgkmcnt(8)
	s_nop 0
	s_waitcnt lgkmcnt(0)
	v_mfma_f32_32x32x16_bf16 v[16:31], v[140:143], v[234:237], v[16:31]
	v_add_f32_e32 v140, 0, v112
	v_add_f32_e32 v140, v113, v140
	v_add_f32_e32 v140, v114, v140
	v_add_f32_e32 v140, v115, v140
	v_add_f32_e32 v140, v116, v140
	v_add_f32_e32 v140, v117, v140
	v_add_f32_e32 v140, v118, v140
	v_mfma_f32_32x32x16_bf16 v[0:15], v[164:167], v[144:147], v[0:15]
	v_add_f32_e32 v140, v119, v140
	v_add_f32_e32 v140, v120, v140
	v_add_f32_e32 v140, v121, v140
	v_add_f32_e32 v140, v122, v140
	v_add_f32_e32 v140, v123, v140
	v_add_f32_e32 v140, v124, v140
	v_add_f32_e32 v140, v125, v140
	v_mfma_f32_32x32x16_bf16 v[48:63], v[164:167], v[182:185], v[48:63]
	v_add_f32_e32 v140, v126, v140
	v_cvt_pk_bf16_f32 v144, v112, v113
	v_cvt_pk_bf16_f32 v145, v114, v115
	v_cvt_pk_bf16_f32 v146, v116, v117
	v_cvt_pk_bf16_f32 v147, v118, v119
	v_mfma_f32_32x32x16_bf16 v[32:47], v[164:167], v[186:189], v[32:47]
	v_mfma_f32_32x32x16_bf16 v[16:31], v[164:167], v[214:217], v[16:31]
	v_add_f32_e32 v164, v127, v140
	v_cvt_pk_bf16_f32 v140, v120, v121
	v_cvt_pk_bf16_f32 v141, v122, v123
	v_cvt_pk_bf16_f32 v142, v124, v125
	v_cvt_pk_bf16_f32 v143, v126, v127
	v_mfma_f32_32x32x16_bf16 v[0:15], v[160:163], v[218:221], v[0:15]
	s_waitcnt vmcnt(3)
	s_cbranch_vccz .Ldma_w3
	s_waitcnt vmcnt(0)
